# GEMM1 column rotation table re-derived from the real per-column activation map (gelu tiles spread 1/2/1/2 over the four workgroup classes instead of 0/3/0/3)
# speedup vs baseline: 1.0027x; 1.0027x over previous
.LBB0_263:
	s_add_i32 s58, s58, 1
	s_mul_i32 s0, s58, s31
	s_mul_hi_u32 s1, s58, s3
	s_add_i32 s1, s1, s0
	s_mul_i32 s0, s58, s3
	s_add_u32 s14, s0, s2
	s_addc_u32 s15, s1, s7
	v_mov_b64_e32 v[2:3], 0x900
	v_cmp_lt_i64_e64 s[40:41], s[14:15], v[2:3]
	v_mov_b64_e32 v[2:3], 0x8ff
	v_cmp_gt_i64_e32 vcc, s[14:15], v[2:3]
	s_cbranch_vccnz .LBB0_265
	s_ashr_i32 s0, s14, 31
	s_lshr_b32 s0, s0, 29
	s_add_i32 s0, s14, s0
	s_ashr_i32 s1, s0, 3
	s_and_b32 s0, s0, -8
	s_sub_i32 s0, s14, s0
	s_cmp_lt_i32 s0, 0
	s_cselect_b32 s14, s83, 0x120
	s_mul_i32 s0, s0, s14
	s_add_i32 s0, s0, s1
	s_mul_hi_i32 s1, s0, 0x2aaaaaab
	s_lshr_b32 s14, s1, 31
	s_ashr_i32 s1, s1, 4
	s_add_i32 s1, s1, s14
	s_lshl_b32 s14, s1, 3
	s_sub_i32 s15, 0xc0, s14
	s_min_i32 s15, s15, 8
	s_abs_i32 s16, s15
	v_cvt_f32_u32_e32 v2, s16
	s_sub_i32 s35, 0, s16
	s_mulk_i32 s1, 0x60
	s_sub_i32 s0, s0, s1
	v_rcp_iflag_f32_e32 v2, v2
	s_abs_i32 s1, s0
	s_xor_b32 s17, s0, s15
	s_ashr_i32 s17, s17, 31
	v_mul_f32_e32 v2, 0x4f7ffffe, v2
	v_cvt_u32_f32_e32 v2, v2
	s_nop 0
	v_readfirstlane_b32 s38, v2
	s_mul_i32 s35, s35, s38
	s_mul_hi_u32 s35, s38, s35
	s_add_i32 s38, s38, s35
	s_mul_hi_u32 s35, s1, s38
	s_mul_i32 s38, s35, s16
	s_sub_i32 s1, s1, s38
	s_add_i32 s39, s35, 1
	s_sub_i32 s38, s1, s16
	s_cmp_ge_u32 s1, s16
	s_cselect_b32 s35, s39, s35
	s_cselect_b32 s1, s38, s1
	s_add_i32 s38, s35, 1
	s_cmp_ge_u32 s1, s16
	s_cselect_b32 s1, s38, s35
	s_xor_b32 s1, s1, s17
	s_sub_i32 s48, s1, s17
	s_mul_i32 s1, s48, s15
	s_sub_i32 s0, s0, s1
	s_add_i32 s50, s14, s0
	s_lshl_b32 s1, s58, 1
	s_lshr_b32 s1, 0x3e540, s1
	s_add_i32 s1, s1, s48
	s_and_b32 s1, s1, 3
	s_and_b32 s48, s48, -4
	s_or_b32 s48, s48, s1
